# mix2: one static s_setprio 1 for waves 4-7 for the whole phase, per-section priority flips in the chunk loop deleted
# speedup vs baseline: 1.0097x; 1.0028x over previous
; #define LAS __attribute__((address_space(3)))
; __device__ void phase_mix2(const Params& P, LAS unsigned char* lds, const int G, const int bid) {
;     unsigned char* dob = (unsigned char*)P.out; const float* tot = (const float*)(dob + DO_TOT); const float* tots = (const float*)(dob + DO_TOTS);
;     for (int it = bid; it < 256; it += G) {
;         const int sg = it >> 3, hd = it & 7;
;         const int seqlen = sg < 16 ? 8192 : 2048; const int s = sg < 16 ? (sg & 7) : ((sg - 16) & 1), nseg = sg < 16 ? 8 : 2; const int sg0 = sg - s;
;         for (int pass = 0; pass < 2; ++pass) { const int dir = pass ? 0 : 1;
.LBB0_69:
	s_and_b64 vcc, exec, s[2:3]
	s_cbranch_vccz .LBB0_371
	v_readlane_b32 s0, v255, 19
	s_cmpk_gt_i32 s0, 0xff
	s_cbranch_scc1 .LBB0_371
	v_readfirstlane_b32 s0, v162
	s_nop 3
	s_lshr_b32 s0, s0, 6
	s_cmp_ge_u32 s0, 4
	s_cbranch_scc0 .Lmix_prio_done
	s_setprio 1
.Lmix_prio_done:
	s_add_u32 s52, s20, 0x4600000
	s_addc_u32 s53, s21, 0
	s_add_u32 s28, s20, 0x5f00000
	s_addc_u32 s96, s21, 0
	s_add_u32 s34, s20, 0x4000000
	s_addc_u32 s35, s21, 0
	v_readlane_b32 s24, v255, 19
	s_branch .LBB0_73

; #define TRFRAG(img, c, ks) trfrag_(lds, (img) + 256u * (32u * (ks)) + TRA(c, 0), (img) + 256u * (32u * (ks) + 4u) + TRA(c, 1))
; #define MFMA16(a, b, c) __builtin_amdgcn_mfma_f32_16x16x32_bf16((a), (b), (c), 0, 0, 0)
; __device__ void mix_sweep(const Params& P, LAS unsigned char* lds, int tok0, int pos0, int seqlen, int hd, int dir, bool state_only, bool final_pass,
;                           f32x4 (&Cacc)[9], float& m_state, float& aseg_sum, float lgam) {
;     ...
;         if (!state_only) {
;             int irow = 16 * w + fr; asm volatile("" : "+v"(irow));
;             bf16x8 qf[4];
; #pragma unroll
;             for (int s = 0; s < 4; ++s) qf[s] = ROWFRAG(IMG_Q, 16 * w, s);
;             f32x4 O[9];
;             __builtin_amdgcn_s_setprio(1);
; #pragma unroll
;             for (int nt = 0; nt < 8; ++nt) { f32x4 a = (f32x4){0.f, 0.f, 0.f, 0.f}; LAUNDER_L16
;                 bf16x8 cf[4];
; #pragma unroll
;                 for (int ks = 0; ks < 4; ++ks) cf[ks] = TRFRAG(IMG_C, nt, ks);
;                 __builtin_amdgcn_sched_barrier(0);
; #pragma unroll
;                 for (int ks = 0; ks < 4; ++ks) a = MFMA16(cf[ks], qf[ks], a);
;                 O[nt] = a; }
.LBB0_105:
	v_mov_b32_e32 v0, s29
	s_waitcnt lgkmcnt(0)
	s_barrier
	ds_read_b32 v156, v0
	v_mov_b32_e32 v188, v219
	v_add_u32_e32 v0, s84, v174
	v_add_u32_e32 v159, s84, v176
	v_add_u32_e32 v157, s84, v175
	ds_read_b128 v[92:95], v0
	ds_read_b128 v[96:99], v157
	v_add_u32_e32 v170, s84, v177
	ds_read_b128 v[100:103], v159
	ds_read_b128 v[88:91], v170
	v_add_u32_e32 v204, v193, v178
	v_xad_u32 v205, v178, 16, v193
	ds_read_b64_tr_b16 v[222:223], v204
	ds_read_b64_tr_b16 v[224:225], v205 offset:1024
	ds_read_b64_tr_b16 v[226:227], v204 offset:8192
	ds_read_b64_tr_b16 v[228:229], v205 offset:9216
	ds_read_b64_tr_b16 v[230:231], v204 offset:16384
	ds_read_b64_tr_b16 v[232:233], v205 offset:17408
	ds_read_b64_tr_b16 v[234:235], v204 offset:24576
	ds_read_b64_tr_b16 v[236:237], v205 offset:25600
	v_xad_u32 v206, v178, 32, v193
	v_xad_u32 v207, v178, 48, v193
	s_waitcnt lgkmcnt(6)
	v_mfma_f32_16x16x32_bf16 v[76:79], v[222:225], v[92:95], 0
	ds_read_b64_tr_b16 v[238:239], v206
	ds_read_b64_tr_b16 v[240:241], v207 offset:1024
	ds_read_b64_tr_b16 v[242:243], v206 offset:8192
	ds_read_b64_tr_b16 v[244:245], v207 offset:9216
	s_waitcnt lgkmcnt(8)
	v_mfma_f32_16x16x32_bf16 v[76:79], v[226:229], v[96:99], v[76:79]
	ds_read_b64_tr_b16 v[124:125], v206 offset:16384
	ds_read_b64_tr_b16 v[126:127], v207 offset:17408
	ds_read_b64_tr_b16 v[128:129], v206 offset:24576
	ds_read_b64_tr_b16 v[130:131], v207 offset:25600
	s_waitcnt lgkmcnt(10)
	v_mfma_f32_16x16x32_bf16 v[76:79], v[230:233], v[100:103], v[76:79]
	s_waitcnt lgkmcnt(8)
	v_mfma_f32_16x16x32_bf16 v[76:79], v[234:237], v[88:91], v[76:79]
	v_xad_u32 v204, v178, 64, v193
	s_movk_i32 s15, 0x50
	v_xad_u32 v205, v178, s15, v193
	s_waitcnt lgkmcnt(6)
	v_mfma_f32_16x16x32_bf16 v[80:83], v[238:241], v[92:95], 0
	ds_read_b64_tr_b16 v[222:223], v204
	ds_read_b64_tr_b16 v[224:225], v205 offset:1024
	ds_read_b64_tr_b16 v[226:227], v204 offset:8192
	ds_read_b64_tr_b16 v[228:229], v205 offset:9216
	s_waitcnt lgkmcnt(8)
	v_mfma_f32_16x16x32_bf16 v[80:83], v[242:245], v[96:99], v[80:83]
	ds_read_b64_tr_b16 v[230:231], v204 offset:16384
	ds_read_b64_tr_b16 v[232:233], v205 offset:17408
	ds_read_b64_tr_b16 v[234:235], v204 offset:24576
	ds_read_b64_tr_b16 v[236:237], v205 offset:25600
	s_waitcnt lgkmcnt(10)
	v_mfma_f32_16x16x32_bf16 v[80:83], v[124:127], v[100:103], v[80:83]
	s_waitcnt lgkmcnt(8)
	v_mfma_f32_16x16x32_bf16 v[80:83], v[128:131], v[88:91], v[80:83]
	s_movk_i32 s15, 0x60
	v_xad_u32 v206, v178, s15, v193
	s_movk_i32 s15, 0x70
	v_xad_u32 v207, v178, s15, v193
	s_waitcnt lgkmcnt(6)
	v_mfma_f32_16x16x32_bf16 v[84:87], v[222:225], v[92:95], 0
	ds_read_b64_tr_b16 v[238:239], v206
	ds_read_b64_tr_b16 v[240:241], v207 offset:1024
	ds_read_b64_tr_b16 v[242:243], v206 offset:8192
	ds_read_b64_tr_b16 v[244:245], v207 offset:9216
	s_waitcnt lgkmcnt(8)
	v_mfma_f32_16x16x32_bf16 v[84:87], v[226:229], v[96:99], v[84:87]
	ds_read_b64_tr_b16 v[124:125], v206 offset:16384
	ds_read_b64_tr_b16 v[126:127], v207 offset:17408
	ds_read_b64_tr_b16 v[128:129], v206 offset:24576
	ds_read_b64_tr_b16 v[130:131], v207 offset:25600
	s_waitcnt lgkmcnt(10)
	v_mfma_f32_16x16x32_bf16 v[84:87], v[230:233], v[100:103], v[84:87]
	s_waitcnt lgkmcnt(8)
	v_mfma_f32_16x16x32_bf16 v[84:87], v[234:237], v[88:91], v[84:87]
	s_movk_i32 s15, 0x80
	v_xad_u32 v204, v178, s15, v193
	s_movk_i32 s15, 0x90
	v_xad_u32 v205, v178, s15, v193
	s_waitcnt lgkmcnt(6)
	v_mfma_f32_16x16x32_bf16 v[104:107], v[238:241], v[92:95], 0
	ds_read_b64_tr_b16 v[222:223], v204
	ds_read_b64_tr_b16 v[224:225], v205 offset:1024
	ds_read_b64_tr_b16 v[226:227], v204 offset:8192
	ds_read_b64_tr_b16 v[228:229], v205 offset:9216
	s_waitcnt lgkmcnt(8)
	v_mfma_f32_16x16x32_bf16 v[104:107], v[242:245], v[96:99], v[104:107]
	ds_read_b64_tr_b16 v[230:231], v204 offset:16384
	ds_read_b64_tr_b16 v[232:233], v205 offset:17408
	ds_read_b64_tr_b16 v[234:235], v204 offset:24576
	ds_read_b64_tr_b16 v[236:237], v205 offset:25600
	s_waitcnt lgkmcnt(10)
	v_mfma_f32_16x16x32_bf16 v[104:107], v[124:127], v[100:103], v[104:107]
	s_waitcnt lgkmcnt(8)
	v_mfma_f32_16x16x32_bf16 v[104:107], v[128:131], v[88:91], v[104:107]
	s_movk_i32 s15, 0xa0
	v_xad_u32 v206, v178, s15, v193
	s_movk_i32 s15, 0xb0
	v_xad_u32 v207, v178, s15, v193
	s_waitcnt lgkmcnt(6)
	v_mfma_f32_16x16x32_bf16 v[108:111], v[222:225], v[92:95], 0
	ds_read_b64_tr_b16 v[238:239], v206
	ds_read_b64_tr_b16 v[240:241], v207 offset:1024
	ds_read_b64_tr_b16 v[242:243], v206 offset:8192
	ds_read_b64_tr_b16 v[244:245], v207 offset:9216
	s_waitcnt lgkmcnt(8)
	v_mfma_f32_16x16x32_bf16 v[108:111], v[226:229], v[96:99], v[108:111]
	ds_read_b64_tr_b16 v[124:125], v206 offset:16384
	ds_read_b64_tr_b16 v[126:127], v207 offset:17408
	ds_read_b64_tr_b16 v[128:129], v206 offset:24576
	ds_read_b64_tr_b16 v[130:131], v207 offset:25600
	s_waitcnt lgkmcnt(10)
; #define LAS __attribute__((address_space(3)))
; #define TRFRAGX(img, ks) trfrag_(lds, (img) + 32u * (32u * (ks)) + FB.txb, (img) + 32u * (32u * (ks) + 4u) + FB.txb)
; #define MFMA16(a, b, c) __builtin_amdgcn_mfma_f32_16x16x32_bf16((a), (b), (c), 0, 0, 0)
; __device__ void mix_sweep(const Params& P, LAS unsigned char* lds, int tok0, int pos0, int seqlen, int hd, int dir, bool state_only, bool final_pass,
;                           f32x4 (&Cacc)[9], float& m_state, float& aseg_sum, float lgam) {
;     ...
;                 O[nt] = a; }
;             { f32x4 a = (f32x4){0.f, 0.f, 0.f, 0.f};
;               if (is_m) {
; #pragma unroll
;                   for (int ks = 0; ks < 4; ++ks) a = MFMA16(TRFRAGX(IMG_CX, ks), qf[ks], a); }
;               O[8] = a; }
;             __builtin_amdgcn_s_setprio(0);
;             const float wi = vwi[irow], rt = vrow[irow];
; #pragma unroll
;             for (int nt = 0; nt < 9; ++nt) O[nt] = O[nt] * wi;
; #pragma unroll
;             for (int nt = 0; nt < 8; ++nt) { f32x4 a = (f32x4){0.f, 0.f, 0.f, 0.f}; bf16x8 kr[4];
; #pragma unroll
;                 for (int s = 0; s < 4; ++s) kr[s] = ROWFRAG(IMG_K, 16 * nt, s);
;                 __builtin_amdgcn_sched_barrier(0);
; #pragma unroll
;                 for (int s = 0; s < 4; ++s) a = MFMA16(kr[s], qf[s], a);
;                 const f32x4 ct = *(const LAS f32x4*)(vcol + 16 * nt + 4 * fg); float p[4];
; #pragma unroll
;                 for (int e = 0; e < 4; ++e) { const int j = 16 * nt + 4 * fg + e;
;                     const bool keep = dir ? (is_m ? (j >= irow) : (j > irow)) : (j <= irow);
;                     const float ex = __builtin_amdgcn_exp2f(rt + ct[e]); p[e] = keep ? a[e] * ex : 0.f; }
	v_mfma_f32_16x16x32_bf16 v[108:111], v[230:233], v[100:103], v[108:111]
	s_waitcnt lgkmcnt(8)
	v_mfma_f32_16x16x32_bf16 v[108:111], v[234:237], v[88:91], v[108:111]
	s_movk_i32 s15, 0xc0
	v_xad_u32 v204, v178, s15, v193
	s_movk_i32 s15, 0xd0
	v_xad_u32 v205, v178, s15, v193
	s_waitcnt lgkmcnt(6)
	v_mfma_f32_16x16x32_bf16 v[112:115], v[238:241], v[92:95], 0
	ds_read_b64_tr_b16 v[222:223], v204
	ds_read_b64_tr_b16 v[224:225], v205 offset:1024
	ds_read_b64_tr_b16 v[226:227], v204 offset:8192
	ds_read_b64_tr_b16 v[228:229], v205 offset:9216
	s_waitcnt lgkmcnt(8)
	v_mfma_f32_16x16x32_bf16 v[112:115], v[242:245], v[96:99], v[112:115]
	ds_read_b64_tr_b16 v[230:231], v204 offset:16384
	ds_read_b64_tr_b16 v[232:233], v205 offset:17408
	ds_read_b64_tr_b16 v[234:235], v204 offset:24576
	ds_read_b64_tr_b16 v[236:237], v205 offset:25600
	s_waitcnt lgkmcnt(10)
	v_mfma_f32_16x16x32_bf16 v[112:115], v[124:127], v[100:103], v[112:115]
	s_waitcnt lgkmcnt(8)
	v_mfma_f32_16x16x32_bf16 v[112:115], v[128:131], v[88:91], v[112:115]
	s_movk_i32 s15, 0xe0
	v_xad_u32 v206, v178, s15, v193
	s_movk_i32 s15, 0xf0
	v_xad_u32 v207, v178, s15, v193
	s_waitcnt lgkmcnt(6)
	v_mfma_f32_16x16x32_bf16 v[116:119], v[222:225], v[92:95], 0
	ds_read_b64_tr_b16 v[238:239], v206
	ds_read_b64_tr_b16 v[240:241], v207 offset:1024
	ds_read_b64_tr_b16 v[242:243], v206 offset:8192
	ds_read_b64_tr_b16 v[244:245], v207 offset:9216
	s_waitcnt lgkmcnt(8)
	v_mfma_f32_16x16x32_bf16 v[116:119], v[226:229], v[96:99], v[116:119]
	ds_read_b64_tr_b16 v[124:125], v206 offset:16384
	ds_read_b64_tr_b16 v[126:127], v207 offset:17408
	ds_read_b64_tr_b16 v[128:129], v206 offset:24576
	ds_read_b64_tr_b16 v[130:131], v207 offset:25600
	s_waitcnt lgkmcnt(10)
	v_mfma_f32_16x16x32_bf16 v[116:119], v[230:233], v[100:103], v[116:119]
	s_waitcnt lgkmcnt(8)
	v_mfma_f32_16x16x32_bf16 v[116:119], v[234:237], v[88:91], v[116:119]
	s_waitcnt lgkmcnt(6)
	v_mfma_f32_16x16x32_bf16 v[120:123], v[238:241], v[92:95], 0
	s_waitcnt lgkmcnt(4)
	v_mfma_f32_16x16x32_bf16 v[120:123], v[242:245], v[96:99], v[120:123]
	s_waitcnt lgkmcnt(2)
	v_mfma_f32_16x16x32_bf16 v[120:123], v[124:127], v[100:103], v[120:123]
	s_waitcnt lgkmcnt(0)
	v_mfma_f32_16x16x32_bf16 v[120:123], v[128:131], v[88:91], v[120:123]
	s_and_b64 vcc, exec, s[48:49]
	v_mov_b32_e32 v72, 0
	v_mov_b32_e32 v73, 0
	v_mov_b32_e32 v74, 0
	v_mov_b32_e32 v75, 0
	s_cbranch_vccnz .LBB0_107
	v_add_u32_e32 v72, 0x21000, v167
	v_add_u32_e32 v74, 0x21080, v167
	ds_read_b64_tr_b16 v[72:73], v72
	ds_read_b64_tr_b16 v[74:75], v74
	v_add_u32_e32 v124, 0x21400, v167
	v_add_u32_e32 v126, 0x21480, v167
	ds_read_b64_tr_b16 v[124:125], v124
	ds_read_b64_tr_b16 v[126:127], v126
	s_waitcnt lgkmcnt(2)
	v_mfma_f32_16x16x32_bf16 v[72:75], v[72:75], v[92:95], 0
	s_waitcnt lgkmcnt(0)
	v_mfma_f32_16x16x32_bf16 v[72:75], v[124:127], v[96:99], v[72:75]
	v_add_u32_e32 v124, 0x21800, v167
	v_add_u32_e32 v126, 0x21880, v167
	ds_read_b64_tr_b16 v[124:125], v124
	ds_read_b64_tr_b16 v[126:127], v126
	s_waitcnt lgkmcnt(0)
	v_mfma_f32_16x16x32_bf16 v[72:75], v[124:127], v[100:103], v[72:75]
	v_add_u32_e32 v124, 0x21c00, v167
	v_add_u32_e32 v126, 0x21c80, v167
	ds_read_b64_tr_b16 v[124:125], v124
	ds_read_b64_tr_b16 v[126:127], v126
	s_waitcnt lgkmcnt(0)
	v_mfma_f32_16x16x32_bf16 v[72:75], v[124:127], v[88:91], v[72:75]
.LBB0_107:
	v_lshl_add_u32 v220, v188, 2, 0
	v_add_u32_e32 v124, 0x22400, v220
	v_add_u32_e32 v125, 0x22000, v220
	v_add_u32_e32 v132, 0, v174
	ds_read_b32 v158, v124
	ds_read_b32 v171, v125
	ds_read_b128 v[124:127], v132 offset:32768
	v_add_u32_e32 v133, 0, v175
	v_add_u32_e32 v134, 0, v176
	ds_read_b128 v[128:131], v133 offset:32768
	ds_read_b128 v[136:139], v134 offset:32768
	v_add_u32_e32 v135, 0, v177
	ds_read_b128 v[140:143], v135 offset:32768
	s_waitcnt lgkmcnt(3)
	v_mfma_f32_16x16x32_bf16 v[124:127], v[124:127], v[92:95], 0
	s_mov_b64 s[18:19], -1
	s_andn2_b64 vcc, exec, s[12:13]
	s_waitcnt lgkmcnt(2)
	v_mfma_f32_16x16x32_bf16 v[128:131], v[128:131], v[96:99], v[124:127]
	s_waitcnt lgkmcnt(1)
	v_mfma_f32_16x16x32_bf16 v[128:131], v[136:139], v[100:103], v[128:131]
	s_nop 1
	ds_read_b128 v[124:127], v190
	v_cndmask_b32_e64 v136, 0, 1, s[12:13]
	v_cmp_ne_u32_e64 s[48:49], 1, v136
	s_waitcnt lgkmcnt(1)
	v_mfma_f32_16x16x32_bf16 v[128:131], v[140:143], v[88:91], v[128:131]
	v_or_b32_e32 v136, 0, v189
	v_or_b32_e32 v137, 1, v189
	v_or_b32_e32 v138, 2, v189
	v_or_b32_e32 v139, 3, v189
	v_cmp_le_i32_e64 s[16:17], v136, v188
	v_cmp_le_i32_e64 s[18:19], v137, v188
	v_cmp_le_i32_e64 s[50:51], v138, v188
	v_cmp_le_i32_e64 s[54:55], v139, v188
	s_cbranch_vccnz .Lmk_done_0
	v_cndmask_b32_e64 v140, 1, 0, s[42:43]
	v_add_u32_e32 v140, v140, v188
	v_cmp_ge_i32_e64 s[16:17], v136, v140
	v_cmp_ge_i32_e64 s[18:19], v137, v140
	v_cmp_ge_i32_e64 s[50:51], v138, v140
	v_cmp_ge_i32_e64 s[54:55], v139, v140

; #define TRFRAG(img, c, ks) trfrag_(lds, (img) + 256u * (32u * (ks)) + TRA(c, 0), (img) + 256u * (32u * (ks) + 4u) + TRA(c, 1))
; #define MFMA16(a, b, c) __builtin_amdgcn_mfma_f32_16x16x32_bf16((a), (b), (c), 0, 0, 0)
; __device__ void mix_sweep(const Params& P, LAS unsigned char* lds, int tok0, int pos0, int seqlen, int hd, int dir, bool state_only, bool final_pass,
;                           f32x4 (&Cacc)[9], float& m_state, float& aseg_sum, float lgam) {
;     ...
;             __builtin_amdgcn_s_setprio(1);
; #pragma unroll
;             for (int nt = 0; nt < 8; ++nt) { LAUNDER_L16
;                 bf16x8 vf[4];
; #pragma unroll
;                 for (int ks = 0; ks < 4; ++ks) vf[ks] = TRFRAG(IMG_V, nt, ks);
;                 __builtin_amdgcn_sched_barrier(0);
;                 f32x4 a = Cacc[nt] * decay;
; #pragma unroll
;                 for (int ks = 0; ks < 4; ++ks) { O[nt] = MFMA16(vf[ks], pf[ks], O[nt]); a = MFMA16(vf[ks], kf[ks], a); }
;                 Cacc[nt] = a; }
.Lmixpf_skip:
	v_mov_b32_e32 v0, v178
	s_nop 0
	v_xor_b32_e32 v120, 16, v0
	v_add_u32_e32 v80, v246, v0
	v_add_u32_e32 v82, v247, v120
	v_add_u32_e32 v112, v248, v0
	v_add_u32_e32 v114, v249, v120
	v_add_u32_e32 v121, v250, v0
	v_add_u32_e32 v122, v251, v120
	ds_read_b64_tr_b16 v[80:81], v80
	ds_read_b64_tr_b16 v[82:83], v82
	ds_read_b64_tr_b16 v[112:113], v112
	ds_read_b64_tr_b16 v[114:115], v114
	v_add_u32_e32 v0, v252, v0
	v_add_u32_e32 v157, v211, v120
	ds_read_b64_tr_b16 v[120:121], v121
	ds_read_b64_tr_b16 v[122:123], v122
	ds_read_b64_tr_b16 v[170:171], v0
	ds_read_b64_tr_b16 v[172:173], v157
	v_pk_mul_f32 v[34:35], v[34:35], v[156:157] op_sel_hi:[1,0]
	v_pk_mul_f32 v[32:33], v[32:33], v[156:157] op_sel_hi:[1,0]
	s_waitcnt lgkmcnt(6)
	v_mfma_f32_16x16x32_bf16 v[148:151], v[80:83], v[100:103], v[148:151]
	v_mov_b32_e32 v0, v178
	v_mfma_f32_16x16x32_bf16 v[32:35], v[80:83], v[108:111], v[32:35]
	v_xor_b32_e32 v157, 32, v0
	v_xor_b32_e32 v0, 48, v0
	s_waitcnt lgkmcnt(4)
	v_mfma_f32_16x16x32_bf16 v[80:83], v[112:115], v[88:91], v[148:151]
	v_mfma_f32_16x16x32_bf16 v[32:35], v[112:115], v[92:95], v[32:35]
	v_add_u32_e32 v112, v246, v157
	v_add_u32_e32 v114, v247, v0
	ds_read_b64_tr_b16 v[112:113], v112
	ds_read_b64_tr_b16 v[114:115], v114
	s_waitcnt lgkmcnt(4)
	v_mfma_f32_16x16x32_bf16 v[80:83], v[120:123], v[84:87], v[80:83]
	v_add_u32_e32 v148, v250, v157
	v_add_u32_e32 v150, v251, v0
	ds_read_b64_tr_b16 v[148:149], v148
	ds_read_b64_tr_b16 v[150:151], v150
	v_mfma_f32_16x16x32_bf16 v[32:35], v[120:123], v[104:107], v[32:35]
	v_add_u32_e32 v120, v248, v157
	v_add_u32_e32 v122, v249, v0
	ds_read_b64_tr_b16 v[120:121], v120
	ds_read_b64_tr_b16 v[122:123], v122
	v_add_u32_e32 v157, v252, v157
	v_add_u32_e32 v0, v211, v0
	s_waitcnt lgkmcnt(6)
	v_mfma_f32_16x16x32_bf16 v[80:83], v[170:173], v[76:79], v[80:83]
	v_mfma_f32_16x16x32_bf16 v[32:35], v[170:173], v[96:99], v[32:35]
	ds_read_b64_tr_b16 v[170:171], v157
	ds_read_b64_tr_b16 v[172:173], v0
	v_pk_mul_f32 v[30:31], v[30:31], v[156:157] op_sel_hi:[1,0]
	v_pk_mul_f32 v[28:29], v[28:29], v[156:157] op_sel_hi:[1,0]
	s_waitcnt lgkmcnt(6)
	v_mfma_f32_16x16x32_bf16 v[144:147], v[112:115], v[100:103], v[144:147]
	v_mov_b32_e32 v0, v178
	v_mfma_f32_16x16x32_bf16 v[28:31], v[112:115], v[108:111], v[28:31]
	v_xor_b32_e32 v157, 64, v0
	v_xor_b32_e32 v0, 0x50, v0
	s_waitcnt lgkmcnt(2)
	v_mfma_f32_16x16x32_bf16 v[112:115], v[120:123], v[88:91], v[144:147]
	v_mfma_f32_16x16x32_bf16 v[28:31], v[120:123], v[92:95], v[28:31]
	v_add_u32_e32 v120, v246, v157
	v_add_u32_e32 v122, v247, v0
	ds_read_b64_tr_b16 v[120:121], v120
	ds_read_b64_tr_b16 v[122:123], v122
	v_mfma_f32_16x16x32_bf16 v[112:115], v[148:151], v[84:87], v[112:115]
	v_add_u32_e32 v144, v248, v157
	v_add_u32_e32 v146, v249, v0
	ds_read_b64_tr_b16 v[144:145], v144
	v_mfma_f32_16x16x32_bf16 v[28:31], v[148:151], v[104:107], v[28:31]
	v_add_u32_e32 v148, v250, v157
	v_add_u32_e32 v150, v251, v0
	v_add_u32_e32 v157, v252, v157
	v_add_u32_e32 v0, v211, v0
	s_waitcnt lgkmcnt(3)
	v_mfma_f32_16x16x32_bf16 v[112:115], v[170:173], v[76:79], v[112:115]
	ds_read_b64_tr_b16 v[146:147], v146
	ds_read_b64_tr_b16 v[148:149], v148
	ds_read_b64_tr_b16 v[150:151], v150
	v_mfma_f32_16x16x32_bf16 v[28:31], v[170:173], v[96:99], v[28:31]
	ds_read_b64_tr_b16 v[170:171], v157
	ds_read_b64_tr_b16 v[172:173], v0
	v_pk_mul_f32 v[26:27], v[26:27], v[156:157] op_sel_hi:[1,0]
	v_pk_mul_f32 v[24:25], v[24:25], v[156:157] op_sel_hi:[1,0]
	s_waitcnt lgkmcnt(6)
	v_mfma_f32_16x16x32_bf16 v[140:143], v[120:123], v[100:103], v[140:143]
	v_mov_b32_e32 v0, v178
	v_mfma_f32_16x16x32_bf16 v[24:27], v[120:123], v[108:111], v[24:27]
	v_xor_b32_e32 v157, 0x60, v0
	v_xor_b32_e32 v0, 0x70, v0
	s_waitcnt lgkmcnt(4)
	v_mfma_f32_16x16x32_bf16 v[120:123], v[144:147], v[88:91], v[140:143]
	v_mfma_f32_16x16x32_bf16 v[24:27], v[144:147], v[92:95], v[24:27]
	s_nop 1
	v_add_u32_e32 v140, v246, v157
	v_add_u32_e32 v142, v247, v0
	v_add_u32_e32 v144, v248, v157
	s_waitcnt lgkmcnt(2)
	v_mfma_f32_16x16x32_bf16 v[120:123], v[148:151], v[84:87], v[120:123]
	v_add_u32_e32 v146, v249, v0
	ds_read_b64_tr_b16 v[140:141], v140
	ds_read_b64_tr_b16 v[142:143], v142
	ds_read_b64_tr_b16 v[144:145], v144
	v_mfma_f32_16x16x32_bf16 v[24:27], v[148:151], v[104:107], v[24:27]
	v_add_u32_e32 v148, v250, v157
	v_add_u32_e32 v150, v251, v0
	v_add_u32_e32 v157, v252, v157
	v_add_u32_e32 v0, v211, v0
	s_waitcnt lgkmcnt(3)
	v_mfma_f32_16x16x32_bf16 v[120:123], v[170:173], v[76:79], v[120:123]
	ds_read_b64_tr_b16 v[146:147], v146
	ds_read_b64_tr_b16 v[148:149], v148
	ds_read_b64_tr_b16 v[150:151], v150
	v_mfma_f32_16x16x32_bf16 v[24:27], v[170:173], v[96:99], v[24:27]
	ds_read_b64_tr_b16 v[170:171], v157
	ds_read_b64_tr_b16 v[172:173], v0
	v_pk_mul_f32 v[22:23], v[22:23], v[156:157] op_sel_hi:[1,0]
	v_pk_mul_f32 v[20:21], v[20:21], v[156:157] op_sel_hi:[1,0]
	s_waitcnt lgkmcnt(6)
	v_mfma_f32_16x16x32_bf16 v[128:131], v[140:143], v[100:103], v[128:131]
	v_mov_b32_e32 v0, v178
	v_mfma_f32_16x16x32_bf16 v[20:23], v[140:143], v[108:111], v[20:23]
	v_xor_b32_e32 v157, 0x80, v0
	v_xor_b32_e32 v0, 0x90, v0
	v_add_u32_e32 v140, v246, v157
	s_waitcnt lgkmcnt(4)
	v_mfma_f32_16x16x32_bf16 v[128:131], v[144:147], v[88:91], v[128:131]
	v_add_u32_e32 v142, v247, v0
	ds_read_b64_tr_b16 v[140:141], v140
	ds_read_b64_tr_b16 v[142:143], v142
	v_mfma_f32_16x16x32_bf16 v[20:23], v[144:147], v[92:95], v[20:23]
	v_add_u32_e32 v144, v248, v157
	v_add_u32_e32 v146, v249, v0
	ds_read_b64_tr_b16 v[144:145], v144
	s_waitcnt lgkmcnt(5)
; #define TRFRAG(img, c, ks) trfrag_(lds, (img) + 256u * (32u * (ks)) + TRA(c, 0), (img) + 256u * (32u * (ks) + 4u) + TRA(c, 1))
; #define MFMA16(a, b, c) __builtin_amdgcn_mfma_f32_16x16x32_bf16((a), (b), (c), 0, 0, 0)
; __device__ void mix_sweep(const Params& P, LAS unsigned char* lds, int tok0, int pos0, int seqlen, int hd, int dir, bool state_only, bool final_pass,
;                           f32x4 (&Cacc)[9], float& m_state, float& aseg_sum, float lgam) {
;     ...
;             for (int nt = 0; nt < 8; ++nt) { LAUNDER_L16
;                 bf16x8 vf[4];
; #pragma unroll
;                 for (int ks = 0; ks < 4; ++ks) vf[ks] = TRFRAG(IMG_V, nt, ks);
;                 __builtin_amdgcn_sched_barrier(0);
;                 f32x4 a = Cacc[nt] * decay;
; #pragma unroll
;                 for (int ks = 0; ks < 4; ++ks) { O[nt] = MFMA16(vf[ks], pf[ks], O[nt]); a = MFMA16(vf[ks], kf[ks], a); }
;                 Cacc[nt] = a; }
	v_mfma_f32_16x16x32_bf16 v[128:131], v[148:151], v[84:87], v[128:131]
	ds_read_b64_tr_b16 v[146:147], v146
	v_mfma_f32_16x16x32_bf16 v[20:23], v[148:151], v[104:107], v[20:23]
	v_add_u32_e32 v148, v250, v157
	v_add_u32_e32 v150, v251, v0
	v_add_u32_e32 v157, v252, v157
	v_add_u32_e32 v0, v211, v0
	s_waitcnt lgkmcnt(4)
	v_mfma_f32_16x16x32_bf16 v[128:131], v[170:173], v[76:79], v[128:131]
	ds_read_b64_tr_b16 v[148:149], v148
	ds_read_b64_tr_b16 v[150:151], v150
	v_mfma_f32_16x16x32_bf16 v[20:23], v[170:173], v[96:99], v[20:23]
	ds_read_b64_tr_b16 v[170:171], v157
	ds_read_b64_tr_b16 v[172:173], v0
	v_pk_mul_f32 v[18:19], v[18:19], v[156:157] op_sel_hi:[1,0]
	v_pk_mul_f32 v[16:17], v[16:17], v[156:157] op_sel_hi:[1,0]
	s_waitcnt lgkmcnt(6)
	v_mfma_f32_16x16x32_bf16 v[136:139], v[140:143], v[100:103], v[136:139]
	v_mov_b32_e32 v0, v178
	v_mfma_f32_16x16x32_bf16 v[16:19], v[140:143], v[108:111], v[16:19]
	v_xor_b32_e32 v157, 0xa0, v0
	v_xor_b32_e32 v0, 0xb0, v0
	v_add_u32_e32 v140, v246, v157
	s_waitcnt lgkmcnt(4)
	v_mfma_f32_16x16x32_bf16 v[136:139], v[144:147], v[88:91], v[136:139]
	v_add_u32_e32 v142, v247, v0
	ds_read_b64_tr_b16 v[140:141], v140
	ds_read_b64_tr_b16 v[142:143], v142
	v_mfma_f32_16x16x32_bf16 v[16:19], v[144:147], v[92:95], v[16:19]
	v_add_u32_e32 v144, v248, v157
	v_add_u32_e32 v146, v249, v0
	ds_read_b64_tr_b16 v[144:145], v144
	s_waitcnt lgkmcnt(5)
	v_mfma_f32_16x16x32_bf16 v[136:139], v[148:151], v[84:87], v[136:139]
	ds_read_b64_tr_b16 v[146:147], v146
	v_mfma_f32_16x16x32_bf16 v[16:19], v[148:151], v[104:107], v[16:19]
	v_add_u32_e32 v148, v250, v157
	v_add_u32_e32 v150, v251, v0
	v_add_u32_e32 v157, v252, v157
	v_add_u32_e32 v0, v211, v0
	s_waitcnt lgkmcnt(4)
	v_mfma_f32_16x16x32_bf16 v[136:139], v[170:173], v[76:79], v[136:139]
	ds_read_b64_tr_b16 v[148:149], v148
	ds_read_b64_tr_b16 v[150:151], v150
	v_mfma_f32_16x16x32_bf16 v[16:19], v[170:173], v[96:99], v[16:19]
	ds_read_b64_tr_b16 v[170:171], v157
	ds_read_b64_tr_b16 v[172:173], v0
	v_pk_mul_f32 v[14:15], v[14:15], v[156:157] op_sel_hi:[1,0]
	v_pk_mul_f32 v[12:13], v[12:13], v[156:157] op_sel_hi:[1,0]
	s_waitcnt lgkmcnt(6)
	v_mfma_f32_16x16x32_bf16 v[132:135], v[140:143], v[100:103], v[132:135]
	v_mov_b32_e32 v0, v178
	v_mfma_f32_16x16x32_bf16 v[12:15], v[140:143], v[108:111], v[12:15]
	v_xor_b32_e32 v157, 0xc0, v0
	v_xor_b32_e32 v0, 0xd0, v0
	v_add_u32_e32 v140, v246, v157
	s_waitcnt lgkmcnt(4)
	v_mfma_f32_16x16x32_bf16 v[132:135], v[144:147], v[88:91], v[132:135]
	v_add_u32_e32 v142, v247, v0
	ds_read_b64_tr_b16 v[140:141], v140
	ds_read_b64_tr_b16 v[142:143], v142
	v_mfma_f32_16x16x32_bf16 v[12:15], v[144:147], v[92:95], v[12:15]
	v_add_u32_e32 v144, v248, v157
	v_add_u32_e32 v146, v249, v0
	ds_read_b64_tr_b16 v[144:145], v144
	s_waitcnt lgkmcnt(5)
	v_mfma_f32_16x16x32_bf16 v[132:135], v[148:151], v[84:87], v[132:135]
	ds_read_b64_tr_b16 v[146:147], v146
	v_mfma_f32_16x16x32_bf16 v[12:15], v[148:151], v[104:107], v[12:15]
	v_add_u32_e32 v148, v250, v157
	v_add_u32_e32 v150, v251, v0
	v_add_u32_e32 v157, v252, v157
	v_add_u32_e32 v0, v211, v0
	s_waitcnt lgkmcnt(4)
	v_mfma_f32_16x16x32_bf16 v[132:135], v[170:173], v[76:79], v[132:135]
	ds_read_b64_tr_b16 v[148:149], v148
	ds_read_b64_tr_b16 v[150:151], v150
	v_mfma_f32_16x16x32_bf16 v[12:15], v[170:173], v[96:99], v[12:15]
	ds_read_b64_tr_b16 v[170:171], v157
	ds_read_b64_tr_b16 v[172:173], v0
	v_pk_mul_f32 v[10:11], v[10:11], v[156:157] op_sel_hi:[1,0]
	v_pk_mul_f32 v[8:9], v[8:9], v[156:157] op_sel_hi:[1,0]
	s_waitcnt lgkmcnt(6)
	v_mfma_f32_16x16x32_bf16 v[124:127], v[140:143], v[100:103], v[124:127]
	v_mov_b32_e32 v0, v178
	v_mfma_f32_16x16x32_bf16 v[8:11], v[140:143], v[108:111], v[8:11]
	v_xor_b32_e32 v157, 0xe0, v0
	v_xor_b32_e32 v0, 0xf0, v0
	v_add_u32_e32 v140, v246, v157
	s_waitcnt lgkmcnt(4)
	v_mfma_f32_16x16x32_bf16 v[124:127], v[144:147], v[88:91], v[124:127]
	v_add_u32_e32 v142, v247, v0
	ds_read_b64_tr_b16 v[140:141], v140
	ds_read_b64_tr_b16 v[142:143], v142
	v_mfma_f32_16x16x32_bf16 v[8:11], v[144:147], v[92:95], v[8:11]
	v_add_u32_e32 v144, v248, v157
	v_add_u32_e32 v146, v249, v0
	ds_read_b64_tr_b16 v[144:145], v144
	s_waitcnt lgkmcnt(5)
	v_mfma_f32_16x16x32_bf16 v[124:127], v[148:151], v[84:87], v[124:127]
	ds_read_b64_tr_b16 v[146:147], v146
	v_mfma_f32_16x16x32_bf16 v[8:11], v[148:151], v[104:107], v[8:11]
	v_add_u32_e32 v148, v250, v157
	v_add_u32_e32 v150, v251, v0
	v_add_u32_e32 v157, v252, v157
	v_add_u32_e32 v0, v211, v0
	s_waitcnt lgkmcnt(4)
	v_mfma_f32_16x16x32_bf16 v[124:127], v[170:173], v[76:79], v[124:127]
	ds_read_b64_tr_b16 v[148:149], v148
	ds_read_b64_tr_b16 v[150:151], v150
	v_mfma_f32_16x16x32_bf16 v[8:11], v[170:173], v[96:99], v[8:11]
	ds_read_b64_tr_b16 v[170:171], v157
	ds_read_b64_tr_b16 v[172:173], v0
	v_pk_mul_f32 v[6:7], v[6:7], v[156:157] op_sel_hi:[1,0]
	v_pk_mul_f32 v[4:5], v[4:5], v[156:157] op_sel_hi:[1,0]
	s_waitcnt lgkmcnt(6)
	v_mfma_f32_16x16x32_bf16 v[116:119], v[140:143], v[100:103], v[116:119]
	s_mov_b64 s[16:17], -1
	s_and_b64 vcc, exec, s[92:93]
	v_mfma_f32_16x16x32_bf16 v[4:7], v[140:143], v[108:111], v[4:7]
	s_waitcnt lgkmcnt(4)
	v_mfma_f32_16x16x32_bf16 v[116:119], v[144:147], v[88:91], v[116:119]
	v_mfma_f32_16x16x32_bf16 v[4:7], v[144:147], v[92:95], v[4:7]
	s_waitcnt lgkmcnt(2)
	v_mfma_f32_16x16x32_bf16 v[116:119], v[148:151], v[84:87], v[116:119]
	v_mfma_f32_16x16x32_bf16 v[4:7], v[148:151], v[104:107], v[4:7]
	s_waitcnt lgkmcnt(0)
	v_mfma_f32_16x16x32_bf16 v[116:119], v[170:173], v[76:79], v[116:119]
	v_mfma_f32_16x16x32_bf16 v[4:7], v[170:173], v[96:99], v[4:7]
	s_cbranch_vccz .LBB0_365
	s_mov_b64 s[16:17], 0
; #define TRFRAGX(img, ks) trfrag_(lds, (img) + 32u * (32u * (ks)) + FB.txb, (img) + 32u * (32u * (ks) + 4u) + FB.txb)
; #define MFMA16(a, b, c) __builtin_amdgcn_mfma_f32_16x16x32_bf16((a), (b), (c), 0, 0, 0)
; __device__ void mix_sweep(const Params& P, LAS unsigned char* lds, int tok0, int pos0, int seqlen, int hd, int dir, bool state_only, bool final_pass,
;                           f32x4 (&Cacc)[9], float& m_state, float& aseg_sum, float lgam) {
;     ...
;             if (is_m) { f32x4 a = Cacc[8] * decay;
; #pragma unroll
;                 for (int ks = 0; ks < 4; ++ks) { const bf16x8 vx = TRFRAGX(IMG_VX, ks); O[8] = MFMA16(vx, pf[ks], O[8]); a = MFMA16(vx, kf[ks], a); }
;                 Cacc[8] = a; }
;             __builtin_amdgcn_s_setprio(0);
;             float hs = 1.0f;
;             if (is_m) { const float den = __shfl(O[8][0], fr); hs = 1.0f / fmaxf(fabsf(den), vemt[irow]); }
.LBB0_365:
	s_andn2_b64 vcc, exec, s[16:17]
	v_mov_b32_e32 v0, 1.0
	s_cbranch_vccnz .LBB0_367
	v_mov_b32_e32 v140, v158
	v_mov_b32_e32 v141, v158
	v_pk_mul_f32 v[74:75], v[74:75], v[140:141]
	v_mov_b32_e32 v140, v156
	v_mov_b32_e32 v141, v156
	v_add_u32_e32 v0, 0x20000, v167
	v_pk_mul_f32 v[38:39], v[38:39], v[140:141]
	ds_read_b64_tr_b16 v[140:141], v0
	v_add_u32_e32 v0, 0x20080, v167
	ds_read_b64_tr_b16 v[142:143], v0
	v_mov_b32_e32 v159, v158
	v_pk_mul_f32 v[72:73], v[72:73], v[158:159]
	v_add_u32_e32 v0, 0x20400, v167
	v_mov_b32_e32 v157, v156
	s_waitcnt lgkmcnt(0)
	v_mfma_f32_16x16x32_bf16 v[72:75], v[140:143], v[100:103], v[72:75]
	ds_read_b64_tr_b16 v[100:101], v0
	v_add_u32_e32 v0, 0x20480, v167
	ds_read_b64_tr_b16 v[102:103], v0
	v_add_u32_e32 v0, 0x20800, v167
	s_waitcnt lgkmcnt(0)
	v_mfma_f32_16x16x32_bf16 v[72:75], v[100:103], v[88:91], v[72:75]
	ds_read_b64_tr_b16 v[88:89], v0
	v_add_u32_e32 v0, 0x20880, v167
	ds_read_b64_tr_b16 v[90:91], v0
	v_pk_mul_f32 v[36:37], v[36:37], v[156:157]
	v_add_u32_e32 v0, 0x20c00, v167
	s_waitcnt lgkmcnt(0)
	v_mfma_f32_16x16x32_bf16 v[72:75], v[88:91], v[84:87], v[72:75]
	ds_read_b64_tr_b16 v[84:85], v0
	v_add_u32_e32 v0, 0x20c80, v167
	ds_read_b64_tr_b16 v[86:87], v0
	v_mfma_f32_16x16x32_bf16 v[36:39], v[140:143], v[108:111], v[36:39]
	v_mfma_f32_16x16x32_bf16 v[36:39], v[100:103], v[92:95], v[36:39]
	v_mfma_f32_16x16x32_bf16 v[36:39], v[88:91], v[104:107], v[36:39]
	s_waitcnt lgkmcnt(0)
	v_mfma_f32_16x16x32_bf16 v[36:39], v[84:87], v[96:99], v[36:39]
	v_mfma_f32_16x16x32_bf16 v[72:75], v[84:87], v[76:79], v[72:75]
	v_and_or_b32 v0, v203, 64, v169
	v_lshlrev_b32_e32 v0, 2, v0
	s_nop 4
	v_add_u32_e32 v73, 0x22800, v220
	ds_read_b32 v73, v73
	ds_bpermute_b32 v0, v0, v72
	s_waitcnt lgkmcnt(1)
	v_max_f32_e32 v72, v73, v73
	s_waitcnt lgkmcnt(0)
	v_max_f32_e64 v0, |v0|, |v0|
	v_max_f32_e32 v0, v0, v72
	v_rcp_f32_e32 v72, v0
	s_nop 0
	v_fma_f32 v75, -v0, v72, 1.0
	v_fma_f32 v0, v75, v72, v72

; __device__ __forceinline__ float head_lgam(const Params& P, int hd, int dir) { return hd < 4 ? logsigmoidf_(P.in[9][dir * 4 + hd]) : 0.f; }
; __device__ void phase_mix2(const Params& P, LAS unsigned char* lds, const int G, const int bid) {
;     ...
;     for (int it = bid; it < 256; it += G) {
;         const int sg = it >> 3, hd = it & 7;
;         const int seqlen = sg < 16 ? 8192 : 2048; const int s = sg < 16 ? (sg & 7) : ((sg - 16) & 1), nseg = sg < 16 ? 8 : 2; const int sg0 = sg - s;
;         for (int pass = 0; pass < 2; ++pass) { const int dir = pass ? 0 : 1;
;             f32x4 C[9];
; #pragma unroll
;             for (int i = 0; i < 9; ++i) C[i] = (f32x4){0.f, 0.f, 0.f, 0.f};
;             float m = 0.f, as = 0.f;
;             const int nfold = dir ? nseg - 1 - s : s;
;             for (int f = 0; f < nfold; ++f) { const int sp = dir ? nseg - 1 - f : f; const int slot = tot_slot(sg0 + sp, hd, dir);
;                 const float mseg = tots[slot * 2], aseg = tots[slot * 2 + 1];
;                 const float mnew = fmaxf(aseg + m, mseg), d0 = __expf(aseg + m - mnew), d1 = __expf(mseg - mnew);
;                 const float* tp = tot + ((size_t)slot * 512 + threadIdx.x) * 36;
; #pragma unroll
;                 for (int i = 0; i < 9; ++i) C[i] = C[i] * d0 + *(const f32x4*)(tp + 4 * i) * d1;
;                 m = mnew; }
;             mix_sweep(P, lds, sg * 1024, s * 1024, seqlen, hd, dir, false, pass == 1, C, m, as, head_lgam(P, hd, dir));
;         }
;     }
; }
.LBB0_371:
	s_setprio 0
	v_readlane_b32 s80, v255, 20
	v_readlane_b32 s83, v255, 23
	v_readlane_b32 s78, v254, 0
	s_mov_b64 s[2:3], 0
	v_readlane_b32 s88, v253, 63
	v_readlane_b32 s81, v255, 21
	v_readlane_b32 s82, v255, 22
	v_readlane_b32 s79, v254, 1
	s_movk_i32 s83, 0x2000
	s_movk_i32 s95, 0x2c00
	v_readlane_b32 s77, v255, 19
	s_mov_b64 s[56:57], 0
